# combo2 + weight-conversion items: the other 7 row groups touched by dummy loads before the first serialized load
# baseline (speedup 1.0000x reference)
.LBB0_13:
	s_mul_i32 s11, s0, 0xffffea00
	s_add_i32 s11, s11, s27
	s_mul_hi_i32 s27, s11, 0x2e8ba2e9
	s_lshr_b32 s28, s27, 31
	s_ashr_i32 s27, s27, 5
	s_add_i32 s27, s27, s28
	s_mul_i32 s28, s27, 0xb0
	s_and_b32 s10, s0, 3
	s_sub_i32 s11, s11, s28
	s_lshl_b32 s28, s11, 5
	s_mul_i32 s10, s10, 0x2c00000
	s_add_u32 s4, s4, s10
	s_addc_u32 s5, s5, 0
	s_add_u32 s29, s13, s10
	v_or_b32_e32 v0, s28, v7
	s_addc_u32 s30, s14, 0
	s_lshl_b32 s10, s27, 6
	v_ashrrev_i32_e32 v1, 31, v0
	v_lshl_add_u64 v[12:13], v[0:1], 2, s[4:5]
	v_add_u32_e32 v0, s10, v4
	v_mad_i64_i32 v[0:1], s[4:5], v0, s25, v[12:13]
	s_mul_i32 s100, s25, 8
	s_mov_b32 s101, 0
	v_lshl_add_u64 v[62:63], v[0:1], 0, s[100:101]
	global_load_dword v60, v[62:63], off
	v_lshl_add_u64 v[62:63], v[62:63], 0, s[100:101]
	global_load_dword v60, v[62:63], off
	v_lshl_add_u64 v[62:63], v[62:63], 0, s[100:101]
	global_load_dword v60, v[62:63], off
	v_lshl_add_u64 v[62:63], v[62:63], 0, s[100:101]
	global_load_dword v60, v[62:63], off
	v_lshl_add_u64 v[62:63], v[62:63], 0, s[100:101]
	global_load_dword v60, v[62:63], off
	v_lshl_add_u64 v[62:63], v[62:63], 0, s[100:101]
	global_load_dword v60, v[62:63], off
	v_lshl_add_u64 v[62:63], v[62:63], 0, s[100:101]
	global_load_dword v60, v[62:63], off
	flat_load_dwordx4 v[0:3], v[0:1]
	v_add_u32_e32 v8, s10, v14
	v_mad_i64_i32 v[32:33], s[4:5], v8, s25, v[12:13]
	v_add_u32_e32 v8, s10, v15
	v_add_u32_e32 v31, 0x14a8, v22
	s_lshl_b32 s0, s0, 5
	s_and_b32 s0, s0, 0xffffff80
	s_waitcnt vmcnt(0) lgkmcnt(0)
	ds_write2_b32 v22, v0, v1 offset1:1
	ds_write2_b32 v22, v2, v3 offset0:2 offset1:3
	flat_load_dwordx4 v[0:3], v[32:33]
	v_mad_i64_i32 v[32:33], s[4:5], v8, s25, v[12:13]
	v_add_u32_e32 v8, s10, v16
	s_waitcnt vmcnt(0) lgkmcnt(0)
	ds_write2_b32 v23, v0, v1 offset1:1
	ds_write2_b32 v24, v2, v3 offset1:1
	flat_load_dwordx4 v[0:3], v[32:33]
	v_mad_i64_i32 v[32:33], s[4:5], v8, s25, v[12:13]
	v_add_u32_e32 v8, s10, v17
	s_waitcnt vmcnt(0) lgkmcnt(0)
	ds_write2_b32 v25, v0, v1 offset1:1
	ds_write2_b32 v26, v2, v3 offset1:1
	flat_load_dwordx4 v[0:3], v[32:33]
	v_mad_i64_i32 v[32:33], s[4:5], v8, s25, v[12:13]
	v_add_u32_e32 v8, s10, v18
	s_waitcnt vmcnt(0) lgkmcnt(0)
	ds_write2_b32 v27, v0, v1 offset1:1
	ds_write2_b32 v28, v2, v3 offset1:1
	flat_load_dwordx4 v[0:3], v[32:33]
	v_mad_i64_i32 v[32:33], s[4:5], v8, s25, v[12:13]
	v_add_u32_e32 v8, 0x14a0, v22
	s_waitcnt vmcnt(0) lgkmcnt(0)
	ds_write2_b32 v29, v0, v1 offset1:1
	ds_write2_b32 v30, v2, v3 offset1:1
	flat_load_dwordx4 v[0:3], v[32:33]
	v_add_u32_e32 v32, s10, v19
	v_mad_i64_i32 v[32:33], s[4:5], v32, s25, v[12:13]
	s_waitcnt vmcnt(0) lgkmcnt(0)
	ds_write2_b32 v8, v0, v1 offset1:1
	ds_write2_b32 v31, v2, v3 offset1:1
	flat_load_dwordx4 v[0:3], v[32:33]
	v_add_u32_e32 v8, 0x18c0, v22
	v_add_u32_e32 v32, s10, v20
	v_add_u32_e32 v31, 0x18c8, v22
	v_mad_i64_i32 v[12:13], s[4:5], v32, s25, v[12:13]
	s_bfe_u32 s5, s11, 0x70013
	s_bfe_u32 s4, s11, 0x2001d
	s_add_i32 s5, s28, s5
	s_add_i32 s4, s11, s4
	s_ashr_i32 s11, s10, 31
	s_and_b32 s31, s5, 0xff80
	s_sext_i32_i16 s27, s4
	s_lshl_b64 s[4:5], s[10:11], 1
	s_sub_i32 s11, s28, s31
	s_lshl_b32 s10, s27, 6
	s_sext_i32_i16 s11, s11
	s_and_b32 s10, s10, 0xffffff00
	s_add_i32 s0, s0, s11
	s_add_i32 s0, s0, s10
	s_add_u32 s4, s29, s4
	s_addc_u32 s5, s30, s5
	s_waitcnt vmcnt(0) lgkmcnt(0)
	ds_write2_b32 v8, v0, v1 offset1:1
	ds_write2_b32 v31, v2, v3 offset1:1
	flat_load_dwordx4 v[0:3], v[12:13]
	v_add_u32_e32 v12, 0x1ce0, v22
	v_add_u32_e32 v13, 0x1ce8, v22
	v_lshlrev_b32_e32 v8, 1, v6
	v_lshl_add_u64 v[34:35], s[4:5], 0, v[8:9]
	s_waitcnt vmcnt(0) lgkmcnt(0)
	ds_write2_b32 v12, v0, v1 offset1:1
	ds_write2_b32 v13, v2, v3 offset1:1
	s_waitcnt lgkmcnt(0)
	ds_read2_b32 v[0:1], v21 offset1:33
	v_add_u32_e32 v12, s0, v4
	s_waitcnt lgkmcnt(0)
	v_cvt_pk_bf16_f32 v0, v0, v1
	ds_read2_b32 v[2:3], v21 offset0:66 offset1:99
	v_ashrrev_i32_e32 v13, 31, v12
	s_waitcnt lgkmcnt(0)
	v_cvt_pk_bf16_f32 v1, v2, v3
	ds_read2_b32 v[2:3], v21 offset0:132 offset1:165
	v_lshlrev_b64 v[12:13], 12, v[12:13]
	s_waitcnt lgkmcnt(0)
	v_cvt_pk_bf16_f32 v2, v2, v3
	ds_read2_b32 v[32:33], v21 offset0:198 offset1:231
	v_lshl_add_u64 v[12:13], v[34:35], 0, v[12:13]
	s_waitcnt lgkmcnt(0)
	v_cvt_pk_bf16_f32 v3, v32, v33
	flat_store_dwordx4 v[12:13], v[0:3]
	v_add_u32_e32 v32, s0, v14
	ds_read2_b32 v[0:1], v21 offset0:8 offset1:41
	v_ashrrev_i32_e32 v33, 31, v32
	s_waitcnt lgkmcnt(0)
	v_cvt_pk_bf16_f32 v0, v0, v1
	ds_read2_b32 v[2:3], v21 offset0:74 offset1:107
	v_lshlrev_b64 v[32:33], 12, v[32:33]
	s_waitcnt lgkmcnt(0)
	v_cvt_pk_bf16_f32 v1, v2, v3
	ds_read2_b32 v[2:3], v21 offset0:140 offset1:173
	v_lshl_add_u64 v[32:33], v[34:35], 0, v[32:33]
	s_waitcnt lgkmcnt(0)
	v_cvt_pk_bf16_f32 v2, v2, v3
	ds_read2_b32 v[12:13], v21 offset0:206 offset1:239
	s_waitcnt lgkmcnt(0)
	v_cvt_pk_bf16_f32 v3, v12, v13
	flat_store_dwordx4 v[32:33], v[0:3]
	v_add_u32_e32 v32, s0, v15
	ds_read2_b32 v[0:1], v21 offset0:16 offset1:49
	v_ashrrev_i32_e32 v33, 31, v32
	s_waitcnt lgkmcnt(0)
	v_cvt_pk_bf16_f32 v0, v0, v1
	ds_read2_b32 v[2:3], v21 offset0:82 offset1:115
	v_lshlrev_b64 v[32:33], 12, v[32:33]
	s_waitcnt lgkmcnt(0)
	v_cvt_pk_bf16_f32 v1, v2, v3
	ds_read2_b32 v[2:3], v21 offset0:148 offset1:181
	v_lshl_add_u64 v[32:33], v[34:35], 0, v[32:33]
	s_waitcnt lgkmcnt(0)
	v_cvt_pk_bf16_f32 v2, v2, v3
	ds_read2_b32 v[12:13], v21 offset0:214 offset1:247
	s_waitcnt lgkmcnt(0)
	v_cvt_pk_bf16_f32 v3, v12, v13
	flat_store_dwordx4 v[32:33], v[0:3]
	ds_read2_b32 v[0:1], v21 offset0:24 offset1:57
	v_add_u32_e32 v32, s0, v16
	s_waitcnt lgkmcnt(0)
	v_cvt_pk_bf16_f32 v0, v0, v1
	ds_read2_b32 v[2:3], v21 offset0:90 offset1:123
	s_waitcnt lgkmcnt(0)
	v_cvt_pk_bf16_f32 v1, v2, v3
	ds_read2_b32 v[2:3], v21 offset0:156 offset1:189
	v_ashrrev_i32_e32 v33, 31, v32
	s_waitcnt lgkmcnt(0)
	v_cvt_pk_bf16_f32 v2, v2, v3
	ds_read2_b32 v[12:13], v21 offset0:222 offset1:255
	v_lshlrev_b64 v[32:33], 12, v[32:33]
	s_waitcnt lgkmcnt(0)
	v_cvt_pk_bf16_f32 v3, v12, v13
	v_lshl_add_u64 v[12:13], v[34:35], 0, v[32:33]
	flat_store_dwordx4 v[12:13], v[0:3]
	s_waitcnt lgkmcnt(0)

.LBB0_29:
	s_or_saveexec_b64 s[4:5], s[4:5]
	s_lshr_b32 s0, s0, 16
	v_lshlrev_b32_e32 v8, 2, v0
	s_and_b32 s0, s0, 0x7fc0
	v_lshl_add_u64 v[12:13], s[10:11], 0, v[8:9]
	v_mov_b32_e32 v0, 0
	v_mov_b32_e32 v1, 0
	v_mov_b32_e32 v2, 0
	v_mov_b32_e32 v3, 0
	s_xor_b64 exec, exec, s[4:5]
	s_cbranch_execz .LBB0_31
	v_add_u32_e32 v0, s0, v4
	v_mad_i64_i32 v[0:1], s[10:11], v0, s20, v[12:13]
	s_mul_i32 s100, s20, 8
	s_mov_b32 s101, 0
	v_lshl_add_u64 v[62:63], v[0:1], 0, s[100:101]
	global_load_dword v60, v[62:63], off
	v_lshl_add_u64 v[62:63], v[62:63], 0, s[100:101]
	global_load_dword v60, v[62:63], off
	v_lshl_add_u64 v[62:63], v[62:63], 0, s[100:101]
	global_load_dword v60, v[62:63], off
	v_lshl_add_u64 v[62:63], v[62:63], 0, s[100:101]
	global_load_dword v60, v[62:63], off
	v_lshl_add_u64 v[62:63], v[62:63], 0, s[100:101]
	global_load_dword v60, v[62:63], off
	v_lshl_add_u64 v[62:63], v[62:63], 0, s[100:101]
	global_load_dword v60, v[62:63], off
	v_lshl_add_u64 v[62:63], v[62:63], 0, s[100:101]
	global_load_dword v60, v[62:63], off
	flat_load_dwordx4 v[0:3], v[0:1]
	v_add_u32_e32 v8, s0, v14
	s_waitcnt vmcnt(0) lgkmcnt(0)
	ds_write2_b32 v22, v0, v1 offset1:1
	ds_write2_b32 v22, v2, v3 offset0:2 offset1:3
	v_mad_i64_i32 v[0:1], s[10:11], v8, s20, v[12:13]
	flat_load_dwordx4 v[0:3], v[0:1]

.LBB0_44:
	s_and_b64 vcc, exec, s[4:5]
	s_cbranch_vccz .LBB0_46
	s_add_i32 s0, s27, 0xffff5000
	s_mul_i32 s4, s0, 0xba2f
	s_lshr_b32 s4, s4, 28
	s_mul_i32 s5, s4, 0xea00
	v_mov_b32_e32 v0, s21
	s_add_i32 s0, s5, s0
	ds_read_b64 v[0:1], v0
	s_sext_i32_i16 s5, s0
	s_bfe_u32 s5, s5, 0x60019
	s_add_i32 s5, s0, s5
	s_sext_i32_i16 s28, s5
	s_and_b32 s5, s5, 0xffc0
	s_sub_i32 s0, s0, s5
	s_waitcnt lgkmcnt(0)
	v_readfirstlane_b32 s10, v0
	s_mul_i32 s11, s4, 0x2c00000
	v_readfirstlane_b32 s5, v1
	s_add_u32 s10, s10, s11
	s_addc_u32 s11, s5, 0
	s_mul_i32 s4, s4, 0x1600000
	s_sext_i32_i16 s0, s0
	s_add_u32 s29, s15, s4
	s_addc_u32 s30, s16, 0
	s_lshl_b32 s0, s0, 5
	v_or_b32_e32 v0, s0, v7
	s_and_b32 s4, s28, 0xffffffc0
	v_ashrrev_i32_e32 v1, 31, v0
	v_lshl_add_u64 v[12:13], v[0:1], 2, s[10:11]
	v_add_u32_e32 v0, s4, v4
	v_ashrrev_i32_e32 v1, 31, v0
	v_lshlrev_b64 v[0:1], 13, v[0:1]
	v_lshl_add_u64 v[0:1], v[12:13], 0, v[0:1]
	s_mov_b32 s100, 0x10000
	s_mov_b32 s101, 0
	v_lshl_add_u64 v[62:63], v[0:1], 0, s[100:101]
	global_load_dword v60, v[62:63], off
	v_lshl_add_u64 v[62:63], v[62:63], 0, s[100:101]
	global_load_dword v60, v[62:63], off
	v_lshl_add_u64 v[62:63], v[62:63], 0, s[100:101]
	global_load_dword v60, v[62:63], off
	v_lshl_add_u64 v[62:63], v[62:63], 0, s[100:101]
	global_load_dword v60, v[62:63], off
	v_lshl_add_u64 v[62:63], v[62:63], 0, s[100:101]
	global_load_dword v60, v[62:63], off
	v_lshl_add_u64 v[62:63], v[62:63], 0, s[100:101]
	global_load_dword v60, v[62:63], off
	v_lshl_add_u64 v[62:63], v[62:63], 0, s[100:101]
	global_load_dword v60, v[62:63], off
	flat_load_dwordx4 v[0:3], v[0:1]
	v_add_u32_e32 v32, s4, v14
	v_ashrrev_i32_e32 v33, 31, v32
	v_lshlrev_b64 v[32:33], 13, v[32:33]
	v_lshl_add_u64 v[32:33], v[12:13], 0, v[32:33]
	v_add_u32_e32 v8, 0x14a0, v22
	v_add_u32_e32 v31, 0x14a8, v22
	s_ashr_i32 s5, s4, 31
	s_waitcnt vmcnt(0) lgkmcnt(0)
	ds_write2_b32 v22, v0, v1 offset1:1
	ds_write2_b32 v22, v2, v3 offset0:2 offset1:3
	flat_load_dwordx4 v[0:3], v[32:33]
	v_add_u32_e32 v32, s4, v15
	v_ashrrev_i32_e32 v33, 31, v32
	v_lshlrev_b64 v[32:33], 13, v[32:33]
	v_lshl_add_u64 v[32:33], v[12:13], 0, v[32:33]
	s_waitcnt vmcnt(0) lgkmcnt(0)
	ds_write2_b32 v23, v0, v1 offset1:1
	ds_write2_b32 v24, v2, v3 offset1:1
	flat_load_dwordx4 v[0:3], v[32:33]
	v_add_u32_e32 v32, s4, v16
	v_ashrrev_i32_e32 v33, 31, v32
	v_lshlrev_b64 v[32:33], 13, v[32:33]
	v_lshl_add_u64 v[32:33], v[12:13], 0, v[32:33]
	s_waitcnt vmcnt(0) lgkmcnt(0)
	ds_write2_b32 v25, v0, v1 offset1:1
	ds_write2_b32 v26, v2, v3 offset1:1
	flat_load_dwordx4 v[0:3], v[32:33]
	v_add_u32_e32 v32, s4, v17
	v_ashrrev_i32_e32 v33, 31, v32
	v_lshlrev_b64 v[32:33], 13, v[32:33]
	v_lshl_add_u64 v[32:33], v[12:13], 0, v[32:33]
	s_waitcnt vmcnt(0) lgkmcnt(0)
	ds_write2_b32 v27, v0, v1 offset1:1
	ds_write2_b32 v28, v2, v3 offset1:1
	flat_load_dwordx4 v[0:3], v[32:33]
	v_add_u32_e32 v32, s4, v18
	v_ashrrev_i32_e32 v33, 31, v32
	v_lshlrev_b64 v[32:33], 13, v[32:33]
	v_lshl_add_u64 v[32:33], v[12:13], 0, v[32:33]
	s_waitcnt vmcnt(0) lgkmcnt(0)
	ds_write2_b32 v29, v0, v1 offset1:1
	ds_write2_b32 v30, v2, v3 offset1:1
	flat_load_dwordx4 v[0:3], v[32:33]
	v_add_u32_e32 v32, s4, v19
	v_ashrrev_i32_e32 v33, 31, v32
	v_lshlrev_b64 v[32:33], 13, v[32:33]
	v_lshl_add_u64 v[32:33], v[12:13], 0, v[32:33]
	s_waitcnt vmcnt(0) lgkmcnt(0)
	ds_write2_b32 v8, v0, v1 offset1:1
	ds_write2_b32 v31, v2, v3 offset1:1
	flat_load_dwordx4 v[0:3], v[32:33]
	v_add_u32_e32 v32, s4, v20
	v_ashrrev_i32_e32 v33, 31, v32
	v_add_u32_e32 v8, 0x18c0, v22
	v_lshlrev_b64 v[32:33], 13, v[32:33]
	v_add_u32_e32 v31, 0x18c8, v22
	v_lshl_add_u64 v[12:13], v[12:13], 0, v[32:33]
	s_lshl_b64 s[4:5], s[4:5], 1
	s_add_u32 s4, s29, s4
	s_addc_u32 s5, s30, s5
	s_waitcnt vmcnt(0) lgkmcnt(0)
	ds_write2_b32 v8, v0, v1 offset1:1
	ds_write2_b32 v31, v2, v3 offset1:1
	flat_load_dwordx4 v[0:3], v[12:13]
	v_add_u32_e32 v8, 0x1ce0, v22
	v_add_u32_e32 v12, 0x1ce8, v22
	v_add_u32_e32 v31, s0, v4
	s_waitcnt vmcnt(0) lgkmcnt(0)
	ds_write2_b32 v8, v0, v1 offset1:1
	ds_write2_b32 v12, v2, v3 offset1:1
	s_waitcnt lgkmcnt(0)
	ds_read2_b32 v[0:1], v21 offset1:33
	v_lshlrev_b32_e32 v8, 1, v6
	s_waitcnt lgkmcnt(0)
	v_cvt_pk_bf16_f32 v0, v0, v1
	ds_read2_b32 v[2:3], v21 offset0:66 offset1:99
	v_lshl_add_u64 v[32:33], s[4:5], 0, v[8:9]
	s_waitcnt lgkmcnt(0)
	v_cvt_pk_bf16_f32 v1, v2, v3
	ds_read2_b32 v[2:3], v21 offset0:132 offset1:165
	v_mad_i64_i32 v[34:35], s[4:5], v31, s22, v[32:33]
	s_waitcnt lgkmcnt(0)
	v_cvt_pk_bf16_f32 v2, v2, v3
	ds_read2_b32 v[12:13], v21 offset0:198 offset1:231
	s_waitcnt lgkmcnt(0)
	v_cvt_pk_bf16_f32 v3, v12, v13
	flat_store_dwordx4 v[34:35], v[0:3]
	ds_read2_b32 v[0:1], v21 offset0:8 offset1:41
	v_add_u32_e32 v8, s0, v16
	s_waitcnt lgkmcnt(0)
	v_cvt_pk_bf16_f32 v0, v0, v1
	ds_read2_b32 v[2:3], v21 offset0:74 offset1:107
	s_waitcnt lgkmcnt(0)
	v_cvt_pk_bf16_f32 v1, v2, v3
	ds_read2_b32 v[2:3], v21 offset0:140 offset1:173
	s_waitcnt lgkmcnt(0)
	v_cvt_pk_bf16_f32 v2, v2, v3
	v_add_u32_e32 v3, s0, v14
	v_mad_i64_i32 v[34:35], s[4:5], v3, s22, v[32:33]
	ds_read2_b32 v[12:13], v21 offset0:206 offset1:239
	s_waitcnt lgkmcnt(0)
	v_cvt_pk_bf16_f32 v3, v12, v13
	flat_store_dwordx4 v[34:35], v[0:3]
	ds_read2_b32 v[0:1], v21 offset0:16 offset1:49
	s_waitcnt lgkmcnt(0)
	v_cvt_pk_bf16_f32 v0, v0, v1
	ds_read2_b32 v[2:3], v21 offset0:82 offset1:115
	s_waitcnt lgkmcnt(0)
	v_cvt_pk_bf16_f32 v1, v2, v3
	ds_read2_b32 v[2:3], v21 offset0:148 offset1:181
	s_waitcnt lgkmcnt(0)
	v_cvt_pk_bf16_f32 v2, v2, v3
	v_add_u32_e32 v3, s0, v15
	v_mad_i64_i32 v[34:35], s[4:5], v3, s22, v[32:33]
	ds_read2_b32 v[12:13], v21 offset0:214 offset1:247
	s_waitcnt lgkmcnt(0)
	v_cvt_pk_bf16_f32 v3, v12, v13
	flat_store_dwordx4 v[34:35], v[0:3]
	ds_read2_b32 v[0:1], v21 offset0:24 offset1:57
	s_waitcnt lgkmcnt(0)
	v_cvt_pk_bf16_f32 v0, v0, v1
	ds_read2_b32 v[2:3], v21 offset0:90 offset1:123
	s_waitcnt lgkmcnt(0)
	v_cvt_pk_bf16_f32 v1, v2, v3
	ds_read2_b32 v[2:3], v21 offset0:156 offset1:189
	s_waitcnt lgkmcnt(0)
	v_cvt_pk_bf16_f32 v2, v2, v3
	ds_read2_b32 v[12:13], v21 offset0:222 offset1:255
	s_waitcnt lgkmcnt(0)
	v_cvt_pk_bf16_f32 v3, v12, v13
	v_mad_i64_i32 v[12:13], s[4:5], v8, s22, v[32:33]
	flat_store_dwordx4 v[12:13], v[0:3]
	s_waitcnt lgkmcnt(0)

.LBB0_1102:
	s_mul_i32 s13, s21, 0xffffea00
	s_add_i32 s13, s13, s38
	s_mul_hi_i32 s20, s13, 0x2e8ba2e9
	s_lshr_b32 s24, s20, 31
	s_ashr_i32 s20, s20, 5
	s_add_i32 s24, s20, s24
	s_mul_i32 s20, s24, 0xb0
	s_and_b32 s12, s21, 3
	s_sub_i32 s13, s13, s20
	s_lshl_b32 s40, s13, 5
	s_mul_i32 s12, s12, 0x2c00000
	s_add_u32 s38, s4, s12
	s_addc_u32 s39, s5, 0
	s_add_u32 s5, s22, s12
	s_addc_u32 s20, s23, 0
	s_bfe_u32 s12, s13, 0x70013
	s_bfe_u32 s4, s13, 0x2001d
	s_add_i32 s12, s40, s12
	s_add_i32 s4, s13, s4
	s_and_b32 s12, s12, 0xff80
	s_sext_i32_i16 s4, s4
	s_sub_i32 s12, s40, s12
	s_lshl_b32 s13, s21, 5
	v_lshlrev_b32_e32 v0, 2, v8
	s_lshl_b32 s4, s4, 6
	s_sext_i32_i16 s12, s12
	s_and_b32 s13, s13, 0xffffff80
	v_and_b32_e32 v1, 28, v0
	s_and_b32 s4, s4, 0xffffff00
	s_add_i32 s12, s13, s12
	v_or_b32_e32 v0, s40, v1
	s_add_i32 s4, s12, s4
	s_lshl_b32 s12, s24, 6
	v_ashrrev_i32_e32 v9, 3, v8
	v_lshlrev_b32_e32 v6, 2, v1
	v_ashrrev_i32_e32 v1, 31, v0
	v_lshl_add_u64 v[4:5], v[0:1], 2, s[38:39]
	v_add_u32_e32 v7, s12, v9
	s_movk_i32 s13, 0x5800
	v_mad_i64_i32 v[0:1], s[38:39], v7, s13, v[4:5]
	s_mul_i32 s100, s13, 8
	s_mov_b32 s101, 0
	v_lshl_add_u64 v[62:63], v[0:1], 0, s[100:101]
	global_load_dword v60, v[62:63], off
	v_lshl_add_u64 v[62:63], v[62:63], 0, s[100:101]
	global_load_dword v60, v[62:63], off
	v_lshl_add_u64 v[62:63], v[62:63], 0, s[100:101]
	global_load_dword v60, v[62:63], off
	v_lshl_add_u64 v[62:63], v[62:63], 0, s[100:101]
	global_load_dword v60, v[62:63], off
	v_lshl_add_u64 v[62:63], v[62:63], 0, s[100:101]
	global_load_dword v60, v[62:63], off
	v_lshl_add_u64 v[62:63], v[62:63], 0, s[100:101]
	global_load_dword v60, v[62:63], off
	v_lshl_add_u64 v[62:63], v[62:63], 0, s[100:101]
	global_load_dword v60, v[62:63], off
	flat_load_dwordx4 v[0:3], v[0:1]
	v_mul_lo_u32 v10, v9, s92
	v_add3_u32 v6, s17, v6, v10
	v_add_u32_e32 v10, 0x2000, v6
	v_add_u32_e32 v11, 0x2420, v6
	v_add_u32_e32 v12, 0x2840, v6
	v_add_u32_e32 v13, 0x2c60, v6
	s_waitcnt vmcnt(0) lgkmcnt(0)
	ds_write2_b32 v10, v0, v1 offset1:1
	v_add_u32_e32 v0, 0x2008, v6
	v_add_u32_e32 v10, 8, v9
	ds_write2_b32 v0, v2, v3 offset1:1
	v_add_u32_e32 v0, s12, v10
	v_mad_i64_i32 v[0:1], s[38:39], v0, s13, v[4:5]
	flat_load_dwordx4 v[0:3], v[0:1]
	s_waitcnt vmcnt(0) lgkmcnt(0)
	ds_write2_b32 v11, v0, v1 offset1:1
	v_add_u32_e32 v0, 0x2428, v6
	v_add_u32_e32 v11, 16, v9
	ds_write2_b32 v0, v2, v3 offset1:1
	v_add_u32_e32 v0, s12, v11
	v_mad_i64_i32 v[0:1], s[38:39], v0, s13, v[4:5]
	flat_load_dwordx4 v[0:3], v[0:1]
	s_waitcnt vmcnt(0) lgkmcnt(0)
	ds_write2_b32 v12, v0, v1 offset1:1
	v_add_u32_e32 v0, 0x2848, v6
	v_add_u32_e32 v12, 24, v9
	ds_write2_b32 v0, v2, v3 offset1:1
	v_add_u32_e32 v0, s12, v12
	v_mad_i64_i32 v[0:1], s[38:39], v0, s13, v[4:5]
	flat_load_dwordx4 v[0:3], v[0:1]
	s_waitcnt vmcnt(0) lgkmcnt(0)
	ds_write2_b32 v13, v0, v1 offset1:1
	v_add_u32_e32 v0, 0x2c68, v6
	ds_write2_b32 v0, v2, v3 offset1:1
	v_add_u32_e32 v0, 32, v7
	v_mad_i64_i32 v[0:1], s[38:39], v0, s13, v[4:5]
	flat_load_dwordx4 v[0:3], v[0:1]
	v_add_u32_e32 v13, 0x3080, v6
	s_waitcnt vmcnt(0) lgkmcnt(0)
	ds_write2_b32 v13, v0, v1 offset1:1
	v_add_u32_e32 v0, 0x3088, v6
	ds_write2_b32 v0, v2, v3 offset1:1
	v_add_u32_e32 v0, 40, v7
	v_mad_i64_i32 v[0:1], s[38:39], v0, s13, v[4:5]
	flat_load_dwordx4 v[0:3], v[0:1]
	v_add_u32_e32 v13, 0x34a0, v6
	s_waitcnt vmcnt(0) lgkmcnt(0)
	ds_write2_b32 v13, v0, v1 offset1:1
	v_add_u32_e32 v0, 0x34a8, v6
	ds_write2_b32 v0, v2, v3 offset1:1
	v_add_u32_e32 v0, 48, v7
	v_mad_i64_i32 v[0:1], s[38:39], v0, s13, v[4:5]
	flat_load_dwordx4 v[0:3], v[0:1]
	v_add_u32_e32 v13, 0x38c0, v6
	s_waitcnt vmcnt(0) lgkmcnt(0)
	ds_write2_b32 v13, v0, v1 offset1:1
	v_add_u32_e32 v0, 0x38c8, v6
	ds_write2_b32 v0, v2, v3 offset1:1
	v_add_u32_e32 v0, 56, v7
	v_mad_i64_i32 v[0:1], s[38:39], v0, s13, v[4:5]
	flat_load_dwordx4 v[0:3], v[0:1]
	v_add_u32_e32 v4, 0x3ce0, v6
	s_ashr_i32 s13, s12, 31
	s_lshl_b64 s[12:13], s[12:13], 1
	s_add_u32 s12, s5, s12
	s_addc_u32 s13, s20, s13
	s_waitcnt vmcnt(0) lgkmcnt(0)
	ds_write2_b32 v4, v0, v1 offset1:1
	v_add_u32_e32 v0, 0x3ce8, v6
	ds_write2_b32 v0, v2, v3 offset1:1
	v_lshlrev_b32_e32 v0, 3, v8
	v_and_b32_e32 v0, 56, v0
	v_mul_u32_u24_e32 v2, 0x84, v0
	v_lshlrev_b32_e32 v3, 2, v9
	s_waitcnt lgkmcnt(0)
	v_add3_u32 v2, s17, v2, v3
	v_add_u32_e32 v8, 0x2000, v2
	ds_read2_b32 v[2:3], v8 offset1:33
	s_waitcnt lgkmcnt(0)
	v_cvt_pk_bf16_f32 v2, v2, v3
	ds_read2_b32 v[4:5], v8 offset0:66 offset1:99
	s_waitcnt lgkmcnt(0)
	v_cvt_pk_bf16_f32 v3, v4, v5
	ds_read2_b32 v[4:5], v8 offset0:132 offset1:165
	s_waitcnt lgkmcnt(0)
	v_cvt_pk_bf16_f32 v4, v4, v5
	ds_read2_b32 v[6:7], v8 offset0:198 offset1:231
	s_waitcnt lgkmcnt(0)
	v_cvt_pk_bf16_f32 v5, v6, v7
	v_add_u32_e32 v6, s4, v9
	v_lshlrev_b32_e32 v0, 1, v0
	v_mov_b32_e32 v1, v16
	v_ashrrev_i32_e32 v7, 31, v6
	v_lshl_add_u64 v[0:1], s[12:13], 0, v[0:1]
	v_lshlrev_b64 v[6:7], 12, v[6:7]
	v_lshl_add_u64 v[6:7], v[0:1], 0, v[6:7]
	flat_store_dwordx4 v[6:7], v[2:5]
	ds_read2_b32 v[2:3], v8 offset0:8 offset1:41
	s_waitcnt lgkmcnt(0)
	v_cvt_pk_bf16_f32 v2, v2, v3
	ds_read2_b32 v[4:5], v8 offset0:74 offset1:107
	s_waitcnt lgkmcnt(0)
	v_cvt_pk_bf16_f32 v3, v4, v5
	ds_read2_b32 v[4:5], v8 offset0:140 offset1:173
	s_waitcnt lgkmcnt(0)
	v_cvt_pk_bf16_f32 v4, v4, v5
	ds_read2_b32 v[6:7], v8 offset0:206 offset1:239
	s_waitcnt lgkmcnt(0)
	v_cvt_pk_bf16_f32 v5, v6, v7
	v_add_u32_e32 v6, s4, v10
	v_ashrrev_i32_e32 v7, 31, v6
	v_lshlrev_b64 v[6:7], 12, v[6:7]
	v_lshl_add_u64 v[6:7], v[0:1], 0, v[6:7]
	flat_store_dwordx4 v[6:7], v[2:5]
	ds_read2_b32 v[2:3], v8 offset0:16 offset1:49
	s_waitcnt lgkmcnt(0)
	v_cvt_pk_bf16_f32 v2, v2, v3
	ds_read2_b32 v[4:5], v8 offset0:82 offset1:115
	s_waitcnt lgkmcnt(0)
	v_cvt_pk_bf16_f32 v3, v4, v5
	ds_read2_b32 v[4:5], v8 offset0:148 offset1:181
	s_waitcnt lgkmcnt(0)
	v_cvt_pk_bf16_f32 v4, v4, v5
	ds_read2_b32 v[6:7], v8 offset0:214 offset1:247
	s_waitcnt lgkmcnt(0)
	v_cvt_pk_bf16_f32 v5, v6, v7
	v_add_u32_e32 v6, s4, v11
	v_ashrrev_i32_e32 v7, 31, v6
	v_lshlrev_b64 v[6:7], 12, v[6:7]
	v_lshl_add_u64 v[6:7], v[0:1], 0, v[6:7]
	flat_store_dwordx4 v[6:7], v[2:5]
	ds_read2_b32 v[2:3], v8 offset0:24 offset1:57
	s_waitcnt lgkmcnt(0)
	v_cvt_pk_bf16_f32 v2, v2, v3
	ds_read2_b32 v[4:5], v8 offset0:90 offset1:123
	s_waitcnt lgkmcnt(0)
	v_cvt_pk_bf16_f32 v3, v4, v5
	ds_read2_b32 v[4:5], v8 offset0:156 offset1:189
	s_waitcnt lgkmcnt(0)
	v_cvt_pk_bf16_f32 v4, v4, v5
	ds_read2_b32 v[6:7], v8 offset0:222 offset1:255
	s_waitcnt lgkmcnt(0)
	v_cvt_pk_bf16_f32 v5, v6, v7
	v_add_u32_e32 v6, s4, v12
	v_ashrrev_i32_e32 v7, 31, v6
	v_lshlrev_b64 v[6:7], 12, v[6:7]
	v_lshl_add_u64 v[0:1], v[0:1], 0, v[6:7]
	flat_store_dwordx4 v[0:1], v[2:5]
	s_waitcnt lgkmcnt(0)

.LBB0_1127:
	s_cmp_gt_i32 s38, 0xafff
	s_mov_b64 s[4:5], -1
	v_mbcnt_lo_u32_b32 v8, -1, 0
	v_mbcnt_hi_u32_b32 v8, -1, v8
	s_cbranch_scc0 .LBB0_1153
	s_cmp_gt_u32 s38, 0x107ff
	s_cbranch_scc0 .LBB0_1150
	s_cmp_gt_u32 s38, 0x13bff
	s_cbranch_scc0 .LBB0_1131
	s_add_i32 s4, s38, 0xfffec400
	s_and_b32 s24, s4, 0xfffff800
	s_and_b32 s5, s4, 0x7c0
	v_readlane_b32 s4, v254, 4
	s_lshl_b64 s[12:13], s[24:25], 13
	v_ashrrev_i32_e32 v9, 3, v8
	v_mov_b32_e32 v0, s4
	ds_read_b64 v[0:1], v0
	v_add_u32_e32 v2, s5, v9
	v_ashrrev_i32_e32 v3, 31, v2
	v_lshlrev_b64 v[4:5], 13, v[2:3]
	v_mul_lo_u32 v3, v9, s92
	s_waitcnt lgkmcnt(0)
	v_readfirstlane_b32 s20, v0
	v_readfirstlane_b32 s4, v1
	s_add_u32 s20, s20, s12
	s_addc_u32 s21, s4, s13
	s_lshl_b64 s[12:13], s[24:25], 12
	s_add_u32 s12, s34, s12
	s_addc_u32 s13, s35, s13
	s_lshl_b32 s4, s38, 5
	v_lshlrev_b32_e32 v0, 2, v8
	s_and_b32 s4, s4, 0x7e0
	v_and_b32_e32 v0, 28, v0
	v_or_b32_e32 v1, s4, v0
	v_lshlrev_b32_e32 v10, 2, v0
	v_lshlrev_b32_e32 v0, 2, v1
	v_mov_b32_e32 v1, v16
	v_lshl_add_u64 v[0:1], s[20:21], 0, v[0:1]
	v_lshl_add_u64 v[4:5], v[0:1], 0, v[4:5]
	s_mov_b32 s100, 0x10000
	s_mov_b32 s101, 0
	v_lshl_add_u64 v[62:63], v[4:5], 0, s[100:101]
	global_load_dword v60, v[62:63], off
	v_lshl_add_u64 v[62:63], v[62:63], 0, s[100:101]
	global_load_dword v60, v[62:63], off
	v_lshl_add_u64 v[62:63], v[62:63], 0, s[100:101]
	global_load_dword v60, v[62:63], off
	v_lshl_add_u64 v[62:63], v[62:63], 0, s[100:101]
	global_load_dword v60, v[62:63], off
	v_lshl_add_u64 v[62:63], v[62:63], 0, s[100:101]
	global_load_dword v60, v[62:63], off
	v_lshl_add_u64 v[62:63], v[62:63], 0, s[100:101]
	global_load_dword v60, v[62:63], off
	v_lshl_add_u64 v[62:63], v[62:63], 0, s[100:101]
	global_load_dword v60, v[62:63], off
	flat_load_dwordx4 v[4:7], v[4:5]
	v_add3_u32 v10, s17, v10, v3
	v_add_u32_e32 v3, 0x2000, v10
	v_add_u32_e32 v11, 8, v9
	v_add_u32_e32 v12, 16, v9
	v_add_u32_e32 v13, 24, v9
	s_waitcnt vmcnt(0) lgkmcnt(0)
	ds_write2_b32 v3, v4, v5 offset1:1
	v_add_u32_e32 v4, s5, v11
	v_ashrrev_i32_e32 v5, 31, v4
	v_add_u32_e32 v3, 0x2008, v10
	v_lshlrev_b64 v[4:5], 13, v[4:5]
	ds_write2_b32 v3, v6, v7 offset1:1
	v_lshl_add_u64 v[4:5], v[0:1], 0, v[4:5]
	flat_load_dwordx4 v[4:7], v[4:5]
	v_add_u32_e32 v3, 0x2420, v10
	s_waitcnt vmcnt(0) lgkmcnt(0)
	ds_write2_b32 v3, v4, v5 offset1:1
	v_add_u32_e32 v4, s5, v12
	v_ashrrev_i32_e32 v5, 31, v4
	v_add_u32_e32 v3, 0x2428, v10
	v_lshlrev_b64 v[4:5], 13, v[4:5]
	ds_write2_b32 v3, v6, v7 offset1:1
	v_lshl_add_u64 v[4:5], v[0:1], 0, v[4:5]
	flat_load_dwordx4 v[4:7], v[4:5]
	v_add_u32_e32 v3, 0x2840, v10
	s_waitcnt vmcnt(0) lgkmcnt(0)
	ds_write2_b32 v3, v4, v5 offset1:1
	v_add_u32_e32 v4, s5, v13
	v_ashrrev_i32_e32 v5, 31, v4
	v_add_u32_e32 v3, 0x2848, v10
	v_lshlrev_b64 v[4:5], 13, v[4:5]
	ds_write2_b32 v3, v6, v7 offset1:1
	v_lshl_add_u64 v[4:5], v[0:1], 0, v[4:5]
	flat_load_dwordx4 v[4:7], v[4:5]
	v_add_u32_e32 v3, 0x2c60, v10
	s_lshl_b32 s5, s5, 1
	s_add_u32 s12, s12, s5
	s_addc_u32 s13, s13, 0
	s_waitcnt vmcnt(0) lgkmcnt(0)
	ds_write2_b32 v3, v4, v5 offset1:1
	v_add_u32_e32 v4, 32, v2
	v_ashrrev_i32_e32 v5, 31, v4
	v_add_u32_e32 v3, 0x2c68, v10
	v_lshlrev_b64 v[4:5], 13, v[4:5]
	ds_write2_b32 v3, v6, v7 offset1:1
	v_lshl_add_u64 v[4:5], v[0:1], 0, v[4:5]
	flat_load_dwordx4 v[4:7], v[4:5]
	v_add_u32_e32 v3, 0x3080, v10
	s_waitcnt vmcnt(0) lgkmcnt(0)
	ds_write2_b32 v3, v4, v5 offset1:1
	v_add_u32_e32 v4, 40, v2
	v_ashrrev_i32_e32 v5, 31, v4
	v_add_u32_e32 v3, 0x3088, v10
	v_lshlrev_b64 v[4:5], 13, v[4:5]
	ds_write2_b32 v3, v6, v7 offset1:1
	v_lshl_add_u64 v[4:5], v[0:1], 0, v[4:5]
	flat_load_dwordx4 v[4:7], v[4:5]
	v_add_u32_e32 v3, 0x34a0, v10
	s_waitcnt vmcnt(0) lgkmcnt(0)
	ds_write2_b32 v3, v4, v5 offset1:1
	v_add_u32_e32 v4, 48, v2
	v_ashrrev_i32_e32 v5, 31, v4
	v_add_u32_e32 v3, 0x34a8, v10
	v_lshlrev_b64 v[4:5], 13, v[4:5]
	ds_write2_b32 v3, v6, v7 offset1:1
	v_lshl_add_u64 v[4:5], v[0:1], 0, v[4:5]
	flat_load_dwordx4 v[4:7], v[4:5]
	v_add_u32_e32 v3, 0x38c0, v10
	v_add_u32_e32 v2, 56, v2
	s_waitcnt vmcnt(0) lgkmcnt(0)
	ds_write2_b32 v3, v4, v5 offset1:1
	v_add_u32_e32 v3, 0x38c8, v10
	ds_write2_b32 v3, v6, v7 offset1:1
	v_ashrrev_i32_e32 v3, 31, v2
	v_lshlrev_b64 v[2:3], 13, v[2:3]
	v_lshl_add_u64 v[0:1], v[0:1], 0, v[2:3]
	flat_load_dwordx4 v[0:3], v[0:1]
	v_add_u32_e32 v4, 0x3ce0, v10
	s_waitcnt vmcnt(0) lgkmcnt(0)
	ds_write2_b32 v4, v0, v1 offset1:1
	v_add_u32_e32 v0, 0x3ce8, v10
	ds_write2_b32 v0, v2, v3 offset1:1
	v_lshlrev_b32_e32 v0, 3, v8
	v_and_b32_e32 v0, 56, v0
	v_mul_u32_u24_e32 v2, 0x84, v0
	v_lshlrev_b32_e32 v0, 1, v0
	v_mov_b32_e32 v1, v16
	v_lshl_add_u64 v[4:5], s[12:13], 0, v[0:1]
	v_lshlrev_b32_e32 v0, 2, v9
	s_waitcnt lgkmcnt(0)
	v_add3_u32 v0, s17, v2, v0
	v_add_u32_e32 v10, 0x2000, v0
	ds_read2_b32 v[0:1], v10 offset1:33
	s_waitcnt lgkmcnt(0)
	v_cvt_pk_bf16_f32 v0, v0, v1
	ds_read2_b32 v[2:3], v10 offset0:66 offset1:99
	s_waitcnt lgkmcnt(0)
	v_cvt_pk_bf16_f32 v1, v2, v3
	ds_read2_b32 v[2:3], v10 offset0:132 offset1:165
	s_waitcnt lgkmcnt(0)
	v_cvt_pk_bf16_f32 v2, v2, v3
	ds_read2_b32 v[6:7], v10 offset0:198 offset1:231
	s_waitcnt lgkmcnt(0)
	v_cvt_pk_bf16_f32 v3, v6, v7
	v_add_u32_e32 v6, s4, v9
	v_ashrrev_i32_e32 v7, 31, v6
	v_lshlrev_b64 v[6:7], 12, v[6:7]
	v_lshl_add_u64 v[6:7], v[4:5], 0, v[6:7]
	flat_store_dwordx4 v[6:7], v[0:3]
	ds_read2_b32 v[0:1], v10 offset0:8 offset1:41
	s_waitcnt lgkmcnt(0)
	v_cvt_pk_bf16_f32 v0, v0, v1
	ds_read2_b32 v[2:3], v10 offset0:74 offset1:107
	s_waitcnt lgkmcnt(0)
	v_cvt_pk_bf16_f32 v1, v2, v3
	ds_read2_b32 v[2:3], v10 offset0:140 offset1:173
	s_waitcnt lgkmcnt(0)
	v_cvt_pk_bf16_f32 v2, v2, v3
	ds_read2_b32 v[6:7], v10 offset0:206 offset1:239
	s_waitcnt lgkmcnt(0)
	v_cvt_pk_bf16_f32 v3, v6, v7
	v_add_u32_e32 v6, s4, v11
	v_ashrrev_i32_e32 v7, 31, v6
	v_lshlrev_b64 v[6:7], 12, v[6:7]
	v_lshl_add_u64 v[6:7], v[4:5], 0, v[6:7]
	flat_store_dwordx4 v[6:7], v[0:3]
	ds_read2_b32 v[0:1], v10 offset0:16 offset1:49
	s_waitcnt lgkmcnt(0)
	v_cvt_pk_bf16_f32 v0, v0, v1
	ds_read2_b32 v[2:3], v10 offset0:82 offset1:115
	s_waitcnt lgkmcnt(0)
	v_cvt_pk_bf16_f32 v1, v2, v3
	ds_read2_b32 v[2:3], v10 offset0:148 offset1:181
	s_waitcnt lgkmcnt(0)
	v_cvt_pk_bf16_f32 v2, v2, v3
	ds_read2_b32 v[6:7], v10 offset0:214 offset1:247
	s_waitcnt lgkmcnt(0)
	v_cvt_pk_bf16_f32 v3, v6, v7
	v_add_u32_e32 v6, s4, v12
	v_ashrrev_i32_e32 v7, 31, v6
	v_lshlrev_b64 v[6:7], 12, v[6:7]
	v_lshl_add_u64 v[6:7], v[4:5], 0, v[6:7]
	flat_store_dwordx4 v[6:7], v[0:3]
	ds_read2_b32 v[0:1], v10 offset0:24 offset1:57
	s_waitcnt lgkmcnt(0)
	v_cvt_pk_bf16_f32 v0, v0, v1
	ds_read2_b32 v[2:3], v10 offset0:90 offset1:123
	s_waitcnt lgkmcnt(0)
	v_cvt_pk_bf16_f32 v1, v2, v3
	ds_read2_b32 v[2:3], v10 offset0:156 offset1:189
	s_waitcnt lgkmcnt(0)
	v_cvt_pk_bf16_f32 v2, v2, v3
	ds_read2_b32 v[6:7], v10 offset0:222 offset1:255
	s_waitcnt lgkmcnt(0)
	v_cvt_pk_bf16_f32 v3, v6, v7
	v_add_u32_e32 v6, s4, v13
	v_ashrrev_i32_e32 v7, 31, v6
	v_lshlrev_b64 v[6:7], 12, v[6:7]
	v_lshl_add_u64 v[4:5], v[4:5], 0, v[6:7]
	flat_store_dwordx4 v[4:5], v[0:3]
	s_waitcnt lgkmcnt(0)
	s_mov_b64 s[4:5], 0
.LBB0_1131:
	s_andn2_b64 vcc, exec, s[4:5]
	s_cbranch_vccnz .LBB0_1149
	s_add_i32 s12, s38, 0xfffef800
	s_cmpk_gt_u32 s12, 0x19ff
	s_cselect_b64 s[20:21], -1, 0
	s_and_b64 s[4:5], s[20:21], exec
	s_cselect_b32 s4, 0xe600, 0
	s_add_i32 s4, s4, s12
	s_sext_i32_i16 s5, s4
	v_readlane_b32 s13, v254, 5
	s_mulk_i32 s5, 0x4ec5
	s_lshr_b32 s12, s5, 31
	v_mov_b32_e32 v0, s13
	s_ashr_i32 s5, s5, 22
	ds_read_b64 v[0:1], v0
	s_add_i32 s12, s5, s12
	s_mul_i32 s5, s12, 0xd0
	s_sub_i32 s4, s4, s5
	s_sext_i32_i16 s13, s4
	s_and_b64 s[4:5], s[20:21], exec
	s_waitcnt lgkmcnt(0)
	v_readfirstlane_b32 s39, v0
	s_cselect_b32 s4, 0x3270000, 0
	v_readfirstlane_b32 s24, v1
	s_add_u32 s4, s39, s4
	v_lshlrev_b32_e32 v0, 2, v8
	s_addc_u32 s5, s24, 0
	s_lshl_b32 s24, s13, 5
	v_and_b32_e32 v1, 28, v0
	v_or_b32_e32 v2, s24, v1
	s_movk_i32 s13, 0x1938
	v_ashrrev_i32_e32 v3, 31, v2
	s_lshl_b32 s12, s12, 6
	v_ashrrev_i32_e32 v9, 3, v8
	v_cmp_gt_i32_e32 vcc, s13, v2
	v_lshl_add_u64 v[6:7], v[2:3], 2, s[4:5]
	v_mov_b32_e32 v0, 0
	v_mov_b32_e32 v2, 0
	v_mov_b32_e32 v3, 0
	v_mov_b32_e32 v4, 0
	v_mov_b32_e32 v5, 0
	s_and_saveexec_b64 s[4:5], vcc
	s_cbranch_execz .LBB0_1134
	v_add_u32_e32 v2, s12, v9
	s_movk_i32 s13, 0x64e0
	v_mad_i64_i32 v[2:3], s[40:41], v2, s13, v[6:7]
	s_mul_i32 s100, s13, 8
	s_mov_b32 s101, 0
	v_lshl_add_u64 v[62:63], v[2:3], 0, s[100:101]
	global_load_dword v60, v[62:63], off
	v_lshl_add_u64 v[62:63], v[62:63], 0, s[100:101]
	global_load_dword v60, v[62:63], off
	v_lshl_add_u64 v[62:63], v[62:63], 0, s[100:101]
	global_load_dword v60, v[62:63], off
	v_lshl_add_u64 v[62:63], v[62:63], 0, s[100:101]
	global_load_dword v60, v[62:63], off
	v_lshl_add_u64 v[62:63], v[62:63], 0, s[100:101]
	global_load_dword v60, v[62:63], off
	v_lshl_add_u64 v[62:63], v[62:63], 0, s[100:101]
	global_load_dword v60, v[62:63], off
	v_lshl_add_u64 v[62:63], v[62:63], 0, s[100:101]
	global_load_dword v60, v[62:63], off
	flat_load_dwordx4 v[2:5], v[2:3]

.LBB0_1150:
	s_andn2_b64 vcc, exec, s[4:5]
	s_cbranch_vccnz .LBB0_1152
	s_add_i32 s4, s38, 0xffff5000
	s_mul_i32 s5, s4, 0xba2f
	s_lshr_b32 s5, s5, 28
	s_mul_i32 s12, s5, 0xea00
	s_add_i32 s4, s12, s4
	s_sext_i32_i16 s12, s4
	s_bfe_u32 s12, s12, 0x60019
	s_add_i32 s12, s4, s12
	s_sext_i32_i16 s13, s12
	s_and_b32 s12, s12, 0xffc0
	s_sub_i32 s4, s4, s12
	v_readlane_b32 s12, v254, 6
	s_mul_i32 s21, s5, 0x2c00000
	s_mul_i32 s5, s5, 0x1600000
	v_mov_b32_e32 v0, s12
	ds_read_b64 v[0:1], v0
	s_sext_i32_i16 s4, s4
	v_ashrrev_i32_e32 v9, 3, v8
	s_waitcnt lgkmcnt(0)
	v_readfirstlane_b32 s20, v0
	v_readfirstlane_b32 s12, v1
	s_add_u32 s40, s20, s21
	s_addc_u32 s41, s12, 0
	s_add_u32 s5, s26, s5
	v_lshlrev_b32_e32 v0, 2, v8
	s_addc_u32 s20, s27, 0
	s_lshl_b32 s4, s4, 5
	s_and_b32 s12, s13, 0xffffffc0
	v_and_b32_e32 v1, 28, v0
	v_or_b32_e32 v0, s4, v1
	v_add_u32_e32 v6, s12, v9
	v_lshlrev_b32_e32 v10, 2, v1
	v_ashrrev_i32_e32 v1, 31, v0
	v_ashrrev_i32_e32 v7, 31, v6
	v_lshl_add_u64 v[4:5], v[0:1], 2, s[40:41]
	v_lshlrev_b64 v[0:1], 13, v[6:7]
	v_lshl_add_u64 v[0:1], v[4:5], 0, v[0:1]
	s_mov_b32 s100, 0x10000
	s_mov_b32 s101, 0
	v_lshl_add_u64 v[62:63], v[0:1], 0, s[100:101]
	global_load_dword v60, v[62:63], off
	v_lshl_add_u64 v[62:63], v[62:63], 0, s[100:101]
	global_load_dword v60, v[62:63], off
	v_lshl_add_u64 v[62:63], v[62:63], 0, s[100:101]
	global_load_dword v60, v[62:63], off
	v_lshl_add_u64 v[62:63], v[62:63], 0, s[100:101]
	global_load_dword v60, v[62:63], off
	v_lshl_add_u64 v[62:63], v[62:63], 0, s[100:101]
	global_load_dword v60, v[62:63], off
	v_lshl_add_u64 v[62:63], v[62:63], 0, s[100:101]
	global_load_dword v60, v[62:63], off
	v_lshl_add_u64 v[62:63], v[62:63], 0, s[100:101]
	global_load_dword v60, v[62:63], off
	flat_load_dwordx4 v[0:3], v[0:1]
	v_mul_lo_u32 v7, v9, s92
	v_add3_u32 v7, s17, v10, v7
	v_add_u32_e32 v10, 0x2000, v7
	v_add_u32_e32 v11, 0x2420, v7
	v_add_u32_e32 v12, 0x2840, v7
	v_add_u32_e32 v13, 0x2c60, v7
	s_ashr_i32 s13, s12, 31
	s_waitcnt vmcnt(0) lgkmcnt(0)
	ds_write2_b32 v10, v0, v1 offset1:1
	v_add_u32_e32 v0, 0x2008, v7
	v_add_u32_e32 v10, 8, v9
	ds_write2_b32 v0, v2, v3 offset1:1
	v_add_u32_e32 v0, s12, v10
	v_ashrrev_i32_e32 v1, 31, v0
	v_lshlrev_b64 v[0:1], 13, v[0:1]
	v_lshl_add_u64 v[0:1], v[4:5], 0, v[0:1]
	flat_load_dwordx4 v[0:3], v[0:1]
	s_waitcnt vmcnt(0) lgkmcnt(0)
	ds_write2_b32 v11, v0, v1 offset1:1
	v_add_u32_e32 v0, 0x2428, v7
	v_add_u32_e32 v11, 16, v9
	ds_write2_b32 v0, v2, v3 offset1:1
	v_add_u32_e32 v0, s12, v11
	v_ashrrev_i32_e32 v1, 31, v0
	v_lshlrev_b64 v[0:1], 13, v[0:1]
	v_lshl_add_u64 v[0:1], v[4:5], 0, v[0:1]
	flat_load_dwordx4 v[0:3], v[0:1]
	s_waitcnt vmcnt(0) lgkmcnt(0)
	ds_write2_b32 v12, v0, v1 offset1:1
	v_add_u32_e32 v0, 0x2848, v7
	v_add_u32_e32 v12, 24, v9
	ds_write2_b32 v0, v2, v3 offset1:1
	v_add_u32_e32 v0, s12, v12
	v_ashrrev_i32_e32 v1, 31, v0
	v_lshlrev_b64 v[0:1], 13, v[0:1]
	v_lshl_add_u64 v[0:1], v[4:5], 0, v[0:1]
	flat_load_dwordx4 v[0:3], v[0:1]
	s_lshl_b64 s[12:13], s[12:13], 1
	s_add_u32 s12, s5, s12
	s_addc_u32 s13, s20, s13
	s_movk_i32 s5, 0x2c00
	s_waitcnt vmcnt(0) lgkmcnt(0)
	ds_write2_b32 v13, v0, v1 offset1:1
	v_add_u32_e32 v0, 0x2c68, v7
	ds_write2_b32 v0, v2, v3 offset1:1
	v_add_u32_e32 v0, 32, v6
	v_ashrrev_i32_e32 v1, 31, v0
	v_lshlrev_b64 v[0:1], 13, v[0:1]
	v_lshl_add_u64 v[0:1], v[4:5], 0, v[0:1]
	flat_load_dwordx4 v[0:3], v[0:1]
	v_add_u32_e32 v13, 0x3080, v7
	s_waitcnt vmcnt(0) lgkmcnt(0)
	ds_write2_b32 v13, v0, v1 offset1:1
	v_add_u32_e32 v0, 0x3088, v7
	ds_write2_b32 v0, v2, v3 offset1:1
	v_add_u32_e32 v0, 40, v6
	v_ashrrev_i32_e32 v1, 31, v0
	v_lshlrev_b64 v[0:1], 13, v[0:1]
	v_lshl_add_u64 v[0:1], v[4:5], 0, v[0:1]
	flat_load_dwordx4 v[0:3], v[0:1]
	v_add_u32_e32 v13, 0x34a0, v7
	s_waitcnt vmcnt(0) lgkmcnt(0)
	ds_write2_b32 v13, v0, v1 offset1:1
	v_add_u32_e32 v0, 0x34a8, v7
	ds_write2_b32 v0, v2, v3 offset1:1
	v_add_u32_e32 v0, 48, v6
	v_ashrrev_i32_e32 v1, 31, v0
	v_lshlrev_b64 v[0:1], 13, v[0:1]
	v_lshl_add_u64 v[0:1], v[4:5], 0, v[0:1]
	flat_load_dwordx4 v[0:3], v[0:1]
	v_add_u32_e32 v13, 0x38c0, v7
	s_waitcnt vmcnt(0) lgkmcnt(0)
	ds_write2_b32 v13, v0, v1 offset1:1
	v_add_u32_e32 v0, 0x38c8, v7
	ds_write2_b32 v0, v2, v3 offset1:1
	v_add_u32_e32 v0, 56, v6
	v_ashrrev_i32_e32 v1, 31, v0
	v_lshlrev_b64 v[0:1], 13, v[0:1]
	v_lshl_add_u64 v[0:1], v[4:5], 0, v[0:1]
	flat_load_dwordx4 v[0:3], v[0:1]
	v_add_u32_e32 v4, 0x3ce0, v7
	s_waitcnt vmcnt(0) lgkmcnt(0)
	ds_write2_b32 v4, v0, v1 offset1:1
	v_add_u32_e32 v0, 0x3ce8, v7
	ds_write2_b32 v0, v2, v3 offset1:1
	v_lshlrev_b32_e32 v0, 3, v8
	v_and_b32_e32 v0, 56, v0
	v_mul_u32_u24_e32 v2, 0x84, v0
	v_lshlrev_b32_e32 v0, 1, v0
	v_mov_b32_e32 v1, v16
	v_lshl_add_u64 v[4:5], s[12:13], 0, v[0:1]
	v_lshlrev_b32_e32 v0, 2, v9
	s_waitcnt lgkmcnt(0)
	v_add3_u32 v0, s17, v2, v0
	v_add_u32_e32 v13, 0x2000, v0
	ds_read2_b32 v[0:1], v13 offset1:33
	s_waitcnt lgkmcnt(0)
	v_cvt_pk_bf16_f32 v0, v0, v1
	ds_read2_b32 v[2:3], v13 offset0:66 offset1:99
	s_waitcnt lgkmcnt(0)
	v_cvt_pk_bf16_f32 v1, v2, v3
	ds_read2_b32 v[2:3], v13 offset0:132 offset1:165
	s_waitcnt lgkmcnt(0)
	v_cvt_pk_bf16_f32 v2, v2, v3
	ds_read2_b32 v[6:7], v13 offset0:198 offset1:231
	s_waitcnt lgkmcnt(0)
	v_cvt_pk_bf16_f32 v3, v6, v7
	v_add_u32_e32 v6, s4, v9
	v_mad_i64_i32 v[6:7], s[12:13], v6, s5, v[4:5]
	flat_store_dwordx4 v[6:7], v[0:3]
	ds_read2_b32 v[0:1], v13 offset0:8 offset1:41
	s_waitcnt lgkmcnt(0)
	v_cvt_pk_bf16_f32 v0, v0, v1
	ds_read2_b32 v[2:3], v13 offset0:74 offset1:107
	s_waitcnt lgkmcnt(0)
	v_cvt_pk_bf16_f32 v1, v2, v3
	ds_read2_b32 v[2:3], v13 offset0:140 offset1:173
	s_waitcnt lgkmcnt(0)
	v_cvt_pk_bf16_f32 v2, v2, v3
	ds_read2_b32 v[6:7], v13 offset0:206 offset1:239
	s_waitcnt lgkmcnt(0)
	v_cvt_pk_bf16_f32 v3, v6, v7
	v_add_u32_e32 v6, s4, v10
	v_mad_i64_i32 v[6:7], s[12:13], v6, s5, v[4:5]
	flat_store_dwordx4 v[6:7], v[0:3]
	ds_read2_b32 v[0:1], v13 offset0:16 offset1:49
	s_waitcnt lgkmcnt(0)
	v_cvt_pk_bf16_f32 v0, v0, v1
	ds_read2_b32 v[2:3], v13 offset0:82 offset1:115
	s_waitcnt lgkmcnt(0)
	v_cvt_pk_bf16_f32 v1, v2, v3
	ds_read2_b32 v[2:3], v13 offset0:148 offset1:181
	s_waitcnt lgkmcnt(0)
	v_cvt_pk_bf16_f32 v2, v2, v3
	ds_read2_b32 v[6:7], v13 offset0:214 offset1:247
	s_waitcnt lgkmcnt(0)
	v_cvt_pk_bf16_f32 v3, v6, v7
	v_add_u32_e32 v6, s4, v11
	v_mad_i64_i32 v[6:7], s[12:13], v6, s5, v[4:5]
	flat_store_dwordx4 v[6:7], v[0:3]
	ds_read2_b32 v[0:1], v13 offset0:24 offset1:57
	s_waitcnt lgkmcnt(0)
	v_cvt_pk_bf16_f32 v0, v0, v1
	ds_read2_b32 v[2:3], v13 offset0:90 offset1:123
	s_waitcnt lgkmcnt(0)
	v_cvt_pk_bf16_f32 v1, v2, v3
	ds_read2_b32 v[2:3], v13 offset0:156 offset1:189
	s_waitcnt lgkmcnt(0)
	v_cvt_pk_bf16_f32 v2, v2, v3
	ds_read2_b32 v[6:7], v13 offset0:222 offset1:255
	s_waitcnt lgkmcnt(0)
	v_cvt_pk_bf16_f32 v3, v6, v7
	v_add_u32_e32 v6, s4, v12
	v_mad_i64_i32 v[4:5], s[4:5], v6, s5, v[4:5]
	flat_store_dwordx4 v[4:5], v[0:3]
	s_waitcnt lgkmcnt(0)

.LBB0_1172:
	s_mul_i32 s13, s21, 0xffffea00
	s_add_i32 s13, s13, s38
	s_mul_hi_i32 s20, s13, 0x2e8ba2e9
	s_lshr_b32 s24, s20, 31
	s_ashr_i32 s20, s20, 5
	s_add_i32 s24, s20, s24
	s_mul_i32 s20, s24, 0xb0
	s_and_b32 s12, s21, 3
	s_sub_i32 s13, s13, s20
	s_lshl_b32 s40, s13, 5
	s_mul_i32 s12, s12, 0x2c00000
	s_add_u32 s38, s4, s12
	s_addc_u32 s39, s5, 0
	s_add_u32 s5, s22, s12
	s_addc_u32 s20, s23, 0
	s_bfe_u32 s12, s13, 0x70013
	s_bfe_u32 s4, s13, 0x2001d
	s_add_i32 s12, s40, s12
	s_add_i32 s4, s13, s4
	s_and_b32 s12, s12, 0xff80
	s_sext_i32_i16 s4, s4
	s_sub_i32 s12, s40, s12
	s_lshl_b32 s13, s21, 5
	v_lshlrev_b32_e32 v0, 2, v8
	s_lshl_b32 s4, s4, 6
	s_sext_i32_i16 s12, s12
	s_and_b32 s13, s13, 0xffffff80
	v_and_b32_e32 v1, 28, v0
	s_and_b32 s4, s4, 0xffffff00
	s_add_i32 s12, s13, s12
	v_or_b32_e32 v0, s40, v1
	s_add_i32 s4, s12, s4
	s_lshl_b32 s12, s24, 6
	v_ashrrev_i32_e32 v9, 3, v8
	v_lshlrev_b32_e32 v6, 2, v1
	v_ashrrev_i32_e32 v1, 31, v0
	v_lshl_add_u64 v[4:5], v[0:1], 2, s[38:39]
	v_add_u32_e32 v7, s12, v9
	s_movk_i32 s13, 0x5800
	v_mad_i64_i32 v[0:1], s[38:39], v7, s13, v[4:5]
	s_mul_i32 s100, s13, 8
	s_mov_b32 s101, 0
	v_lshl_add_u64 v[62:63], v[0:1], 0, s[100:101]
	global_load_dword v60, v[62:63], off
	v_lshl_add_u64 v[62:63], v[62:63], 0, s[100:101]
	global_load_dword v60, v[62:63], off
	v_lshl_add_u64 v[62:63], v[62:63], 0, s[100:101]
	global_load_dword v60, v[62:63], off
	v_lshl_add_u64 v[62:63], v[62:63], 0, s[100:101]
	global_load_dword v60, v[62:63], off
	v_lshl_add_u64 v[62:63], v[62:63], 0, s[100:101]
	global_load_dword v60, v[62:63], off
	v_lshl_add_u64 v[62:63], v[62:63], 0, s[100:101]
	global_load_dword v60, v[62:63], off
	v_lshl_add_u64 v[62:63], v[62:63], 0, s[100:101]
	global_load_dword v60, v[62:63], off
	flat_load_dwordx4 v[0:3], v[0:1]
	v_mul_lo_u32 v10, v9, s92
	v_add3_u32 v6, s17, v6, v10
	v_add_u32_e32 v10, 0x2400, v6
	v_add_u32_e32 v11, 0x2820, v6
	v_add_u32_e32 v12, 0x2c40, v6
	v_add_u32_e32 v13, 0x3060, v6
	s_waitcnt vmcnt(0) lgkmcnt(0)
	ds_write2_b32 v10, v0, v1 offset1:1
	v_add_u32_e32 v0, 0x2408, v6
	v_add_u32_e32 v10, 8, v9
	ds_write2_b32 v0, v2, v3 offset1:1
	v_add_u32_e32 v0, s12, v10
	v_mad_i64_i32 v[0:1], s[38:39], v0, s13, v[4:5]
	flat_load_dwordx4 v[0:3], v[0:1]
	s_waitcnt vmcnt(0) lgkmcnt(0)
	ds_write2_b32 v11, v0, v1 offset1:1
	v_add_u32_e32 v0, 0x2828, v6
	v_add_u32_e32 v11, 16, v9
	ds_write2_b32 v0, v2, v3 offset1:1
	v_add_u32_e32 v0, s12, v11
	v_mad_i64_i32 v[0:1], s[38:39], v0, s13, v[4:5]
	flat_load_dwordx4 v[0:3], v[0:1]
	s_waitcnt vmcnt(0) lgkmcnt(0)
	ds_write2_b32 v12, v0, v1 offset1:1
	v_add_u32_e32 v0, 0x2c48, v6
	v_add_u32_e32 v12, 24, v9
	ds_write2_b32 v0, v2, v3 offset1:1
	v_add_u32_e32 v0, s12, v12
	v_mad_i64_i32 v[0:1], s[38:39], v0, s13, v[4:5]
	flat_load_dwordx4 v[0:3], v[0:1]
	s_waitcnt vmcnt(0) lgkmcnt(0)
	ds_write2_b32 v13, v0, v1 offset1:1
	v_add_u32_e32 v0, 0x3068, v6
	ds_write2_b32 v0, v2, v3 offset1:1
	v_add_u32_e32 v0, 32, v7
	v_mad_i64_i32 v[0:1], s[38:39], v0, s13, v[4:5]
	flat_load_dwordx4 v[0:3], v[0:1]
	v_add_u32_e32 v13, 0x3480, v6
	s_waitcnt vmcnt(0) lgkmcnt(0)
	ds_write2_b32 v13, v0, v1 offset1:1
	v_add_u32_e32 v0, 0x3488, v6
	ds_write2_b32 v0, v2, v3 offset1:1
	v_add_u32_e32 v0, 40, v7
	v_mad_i64_i32 v[0:1], s[38:39], v0, s13, v[4:5]
	flat_load_dwordx4 v[0:3], v[0:1]
	v_add_u32_e32 v13, 0x38a0, v6
	s_waitcnt vmcnt(0) lgkmcnt(0)
	ds_write2_b32 v13, v0, v1 offset1:1
	v_add_u32_e32 v0, 0x38a8, v6
	ds_write2_b32 v0, v2, v3 offset1:1
	v_add_u32_e32 v0, 48, v7
	v_mad_i64_i32 v[0:1], s[38:39], v0, s13, v[4:5]
	flat_load_dwordx4 v[0:3], v[0:1]
	v_add_u32_e32 v13, 0x3cc0, v6
	s_waitcnt vmcnt(0) lgkmcnt(0)
	ds_write2_b32 v13, v0, v1 offset1:1
	v_add_u32_e32 v0, 0x3cc8, v6
	ds_write2_b32 v0, v2, v3 offset1:1
	v_add_u32_e32 v0, 56, v7
	v_mad_i64_i32 v[0:1], s[38:39], v0, s13, v[4:5]
	flat_load_dwordx4 v[0:3], v[0:1]
	v_add_u32_e32 v4, 0x40e0, v6
	s_ashr_i32 s13, s12, 31
	s_lshl_b64 s[12:13], s[12:13], 1
	s_add_u32 s12, s5, s12
	s_addc_u32 s13, s20, s13
	s_waitcnt vmcnt(0) lgkmcnt(0)
	ds_write2_b32 v4, v0, v1 offset1:1
	v_add_u32_e32 v0, 0x40e8, v6
	ds_write2_b32 v0, v2, v3 offset1:1
	v_lshlrev_b32_e32 v0, 3, v8
	v_and_b32_e32 v0, 56, v0
	v_mul_u32_u24_e32 v2, 0x84, v0
	v_lshlrev_b32_e32 v3, 2, v9
	s_waitcnt lgkmcnt(0)
	v_add3_u32 v2, s17, v2, v3
	v_add_u32_e32 v8, 0x2400, v2
	ds_read2_b32 v[2:3], v8 offset1:33
	s_waitcnt lgkmcnt(0)
	v_cvt_pk_bf16_f32 v2, v2, v3
	ds_read2_b32 v[4:5], v8 offset0:66 offset1:99
	s_waitcnt lgkmcnt(0)
	v_cvt_pk_bf16_f32 v3, v4, v5
	ds_read2_b32 v[4:5], v8 offset0:132 offset1:165
	s_waitcnt lgkmcnt(0)
	v_cvt_pk_bf16_f32 v4, v4, v5
	ds_read2_b32 v[6:7], v8 offset0:198 offset1:231
	s_waitcnt lgkmcnt(0)
	v_cvt_pk_bf16_f32 v5, v6, v7
	v_add_u32_e32 v6, s4, v9
	v_lshlrev_b32_e32 v0, 1, v0
	v_mov_b32_e32 v1, v16
	v_ashrrev_i32_e32 v7, 31, v6
	v_lshl_add_u64 v[0:1], s[12:13], 0, v[0:1]
	v_lshlrev_b64 v[6:7], 12, v[6:7]
	v_lshl_add_u64 v[6:7], v[0:1], 0, v[6:7]
	flat_store_dwordx4 v[6:7], v[2:5]
	ds_read2_b32 v[2:3], v8 offset0:8 offset1:41
	s_waitcnt lgkmcnt(0)
	v_cvt_pk_bf16_f32 v2, v2, v3
	ds_read2_b32 v[4:5], v8 offset0:74 offset1:107
	s_waitcnt lgkmcnt(0)
	v_cvt_pk_bf16_f32 v3, v4, v5
	ds_read2_b32 v[4:5], v8 offset0:140 offset1:173
	s_waitcnt lgkmcnt(0)
	v_cvt_pk_bf16_f32 v4, v4, v5
	ds_read2_b32 v[6:7], v8 offset0:206 offset1:239
	s_waitcnt lgkmcnt(0)
	v_cvt_pk_bf16_f32 v5, v6, v7
	v_add_u32_e32 v6, s4, v10
	v_ashrrev_i32_e32 v7, 31, v6
	v_lshlrev_b64 v[6:7], 12, v[6:7]
	v_lshl_add_u64 v[6:7], v[0:1], 0, v[6:7]
	flat_store_dwordx4 v[6:7], v[2:5]
	ds_read2_b32 v[2:3], v8 offset0:16 offset1:49
	s_waitcnt lgkmcnt(0)
	v_cvt_pk_bf16_f32 v2, v2, v3
	ds_read2_b32 v[4:5], v8 offset0:82 offset1:115
	s_waitcnt lgkmcnt(0)
	v_cvt_pk_bf16_f32 v3, v4, v5
	ds_read2_b32 v[4:5], v8 offset0:148 offset1:181
	s_waitcnt lgkmcnt(0)
	v_cvt_pk_bf16_f32 v4, v4, v5
	ds_read2_b32 v[6:7], v8 offset0:214 offset1:247
	s_waitcnt lgkmcnt(0)
	v_cvt_pk_bf16_f32 v5, v6, v7
	v_add_u32_e32 v6, s4, v11
	v_ashrrev_i32_e32 v7, 31, v6
	v_lshlrev_b64 v[6:7], 12, v[6:7]
	v_lshl_add_u64 v[6:7], v[0:1], 0, v[6:7]
	flat_store_dwordx4 v[6:7], v[2:5]
	ds_read2_b32 v[2:3], v8 offset0:24 offset1:57
	s_waitcnt lgkmcnt(0)
	v_cvt_pk_bf16_f32 v2, v2, v3
	ds_read2_b32 v[4:5], v8 offset0:90 offset1:123
	s_waitcnt lgkmcnt(0)
	v_cvt_pk_bf16_f32 v3, v4, v5
	ds_read2_b32 v[4:5], v8 offset0:156 offset1:189
	s_waitcnt lgkmcnt(0)
	v_cvt_pk_bf16_f32 v4, v4, v5
	ds_read2_b32 v[6:7], v8 offset0:222 offset1:255
	s_waitcnt lgkmcnt(0)
	v_cvt_pk_bf16_f32 v5, v6, v7
	v_add_u32_e32 v6, s4, v12
	v_ashrrev_i32_e32 v7, 31, v6
	v_lshlrev_b64 v[6:7], 12, v[6:7]
	v_lshl_add_u64 v[0:1], v[0:1], 0, v[6:7]
	flat_store_dwordx4 v[0:1], v[2:5]
	s_waitcnt lgkmcnt(0)

.LBB0_1197:
	s_cmp_gt_i32 s38, 0xafff
	s_mov_b64 s[4:5], -1
	v_mbcnt_lo_u32_b32 v8, -1, 0
	v_mbcnt_hi_u32_b32 v8, -1, v8
	s_cbranch_scc0 .LBB0_1223
	s_cmp_gt_u32 s38, 0x107ff
	s_cbranch_scc0 .LBB0_1220
	s_cmp_gt_u32 s38, 0x13bff
	s_cbranch_scc0 .LBB0_1201
	s_add_i32 s4, s38, 0xfffec400
	s_and_b32 s24, s4, 0xfffff800
	s_and_b32 s5, s4, 0x7c0
	v_readlane_b32 s4, v254, 4
	s_lshl_b64 s[12:13], s[24:25], 13
	v_ashrrev_i32_e32 v9, 3, v8
	v_mov_b32_e32 v0, s4
	ds_read_b64 v[0:1], v0
	v_add_u32_e32 v2, s5, v9
	v_ashrrev_i32_e32 v3, 31, v2
	v_lshlrev_b64 v[4:5], 13, v[2:3]
	v_mul_lo_u32 v3, v9, s92
	s_waitcnt lgkmcnt(0)
	v_readfirstlane_b32 s20, v0
	v_readfirstlane_b32 s4, v1
	s_add_u32 s20, s20, s12
	s_addc_u32 s21, s4, s13
	s_lshl_b64 s[12:13], s[24:25], 12
	s_add_u32 s12, s34, s12
	s_addc_u32 s13, s35, s13
	s_lshl_b32 s4, s38, 5
	v_lshlrev_b32_e32 v0, 2, v8
	s_and_b32 s4, s4, 0x7e0
	v_and_b32_e32 v0, 28, v0
	v_or_b32_e32 v1, s4, v0
	v_lshlrev_b32_e32 v10, 2, v0
	v_lshlrev_b32_e32 v0, 2, v1
	v_mov_b32_e32 v1, v16
	v_lshl_add_u64 v[0:1], s[20:21], 0, v[0:1]
	v_lshl_add_u64 v[4:5], v[0:1], 0, v[4:5]
	s_mov_b32 s100, 0x10000
	s_mov_b32 s101, 0
	v_lshl_add_u64 v[62:63], v[4:5], 0, s[100:101]
	global_load_dword v60, v[62:63], off
	v_lshl_add_u64 v[62:63], v[62:63], 0, s[100:101]
	global_load_dword v60, v[62:63], off
	v_lshl_add_u64 v[62:63], v[62:63], 0, s[100:101]
	global_load_dword v60, v[62:63], off
	v_lshl_add_u64 v[62:63], v[62:63], 0, s[100:101]
	global_load_dword v60, v[62:63], off
	v_lshl_add_u64 v[62:63], v[62:63], 0, s[100:101]
	global_load_dword v60, v[62:63], off
	v_lshl_add_u64 v[62:63], v[62:63], 0, s[100:101]
	global_load_dword v60, v[62:63], off
	v_lshl_add_u64 v[62:63], v[62:63], 0, s[100:101]
	global_load_dword v60, v[62:63], off
	flat_load_dwordx4 v[4:7], v[4:5]
	v_add3_u32 v10, s17, v10, v3
	v_add_u32_e32 v3, 0x2400, v10
	v_add_u32_e32 v11, 8, v9
	v_add_u32_e32 v12, 16, v9
	v_add_u32_e32 v13, 24, v9
	s_waitcnt vmcnt(0) lgkmcnt(0)
	ds_write2_b32 v3, v4, v5 offset1:1
	v_add_u32_e32 v4, s5, v11
	v_ashrrev_i32_e32 v5, 31, v4
	v_add_u32_e32 v3, 0x2408, v10
	v_lshlrev_b64 v[4:5], 13, v[4:5]
	ds_write2_b32 v3, v6, v7 offset1:1
	v_lshl_add_u64 v[4:5], v[0:1], 0, v[4:5]
	flat_load_dwordx4 v[4:7], v[4:5]
	v_add_u32_e32 v3, 0x2820, v10
	s_waitcnt vmcnt(0) lgkmcnt(0)
	ds_write2_b32 v3, v4, v5 offset1:1
	v_add_u32_e32 v4, s5, v12
	v_ashrrev_i32_e32 v5, 31, v4
	v_add_u32_e32 v3, 0x2828, v10
	v_lshlrev_b64 v[4:5], 13, v[4:5]
	ds_write2_b32 v3, v6, v7 offset1:1
	v_lshl_add_u64 v[4:5], v[0:1], 0, v[4:5]
	flat_load_dwordx4 v[4:7], v[4:5]
	v_add_u32_e32 v3, 0x2c40, v10
	s_waitcnt vmcnt(0) lgkmcnt(0)
	ds_write2_b32 v3, v4, v5 offset1:1
	v_add_u32_e32 v4, s5, v13
	v_ashrrev_i32_e32 v5, 31, v4
	v_add_u32_e32 v3, 0x2c48, v10
	v_lshlrev_b64 v[4:5], 13, v[4:5]
	ds_write2_b32 v3, v6, v7 offset1:1
	v_lshl_add_u64 v[4:5], v[0:1], 0, v[4:5]
	flat_load_dwordx4 v[4:7], v[4:5]
	v_add_u32_e32 v3, 0x3060, v10
	s_lshl_b32 s5, s5, 1
	s_add_u32 s12, s12, s5
	s_addc_u32 s13, s13, 0
	s_waitcnt vmcnt(0) lgkmcnt(0)
	ds_write2_b32 v3, v4, v5 offset1:1
	v_add_u32_e32 v4, 32, v2
	v_ashrrev_i32_e32 v5, 31, v4
	v_add_u32_e32 v3, 0x3068, v10
	v_lshlrev_b64 v[4:5], 13, v[4:5]
	ds_write2_b32 v3, v6, v7 offset1:1
	v_lshl_add_u64 v[4:5], v[0:1], 0, v[4:5]
	flat_load_dwordx4 v[4:7], v[4:5]
	v_add_u32_e32 v3, 0x3480, v10
	s_waitcnt vmcnt(0) lgkmcnt(0)
	ds_write2_b32 v3, v4, v5 offset1:1
	v_add_u32_e32 v4, 40, v2
	v_ashrrev_i32_e32 v5, 31, v4
	v_add_u32_e32 v3, 0x3488, v10
	v_lshlrev_b64 v[4:5], 13, v[4:5]
	ds_write2_b32 v3, v6, v7 offset1:1
	v_lshl_add_u64 v[4:5], v[0:1], 0, v[4:5]
	flat_load_dwordx4 v[4:7], v[4:5]
	v_add_u32_e32 v3, 0x38a0, v10
	s_waitcnt vmcnt(0) lgkmcnt(0)
	ds_write2_b32 v3, v4, v5 offset1:1
	v_add_u32_e32 v4, 48, v2
	v_ashrrev_i32_e32 v5, 31, v4
	v_add_u32_e32 v3, 0x38a8, v10
	v_lshlrev_b64 v[4:5], 13, v[4:5]
	ds_write2_b32 v3, v6, v7 offset1:1
	v_lshl_add_u64 v[4:5], v[0:1], 0, v[4:5]
	flat_load_dwordx4 v[4:7], v[4:5]
	v_add_u32_e32 v3, 0x3cc0, v10
	v_add_u32_e32 v2, 56, v2
	s_waitcnt vmcnt(0) lgkmcnt(0)
	ds_write2_b32 v3, v4, v5 offset1:1
	v_add_u32_e32 v3, 0x3cc8, v10
	ds_write2_b32 v3, v6, v7 offset1:1
	v_ashrrev_i32_e32 v3, 31, v2
	v_lshlrev_b64 v[2:3], 13, v[2:3]
	v_lshl_add_u64 v[0:1], v[0:1], 0, v[2:3]
	flat_load_dwordx4 v[0:3], v[0:1]
	v_add_u32_e32 v4, 0x40e0, v10
	s_waitcnt vmcnt(0) lgkmcnt(0)
	ds_write2_b32 v4, v0, v1 offset1:1
	v_add_u32_e32 v0, 0x40e8, v10
	ds_write2_b32 v0, v2, v3 offset1:1
	v_lshlrev_b32_e32 v0, 3, v8
	v_and_b32_e32 v0, 56, v0
	v_mul_u32_u24_e32 v2, 0x84, v0
	v_lshlrev_b32_e32 v0, 1, v0
	v_mov_b32_e32 v1, v16
	v_lshl_add_u64 v[4:5], s[12:13], 0, v[0:1]
	v_lshlrev_b32_e32 v0, 2, v9
	s_waitcnt lgkmcnt(0)
	v_add3_u32 v0, s17, v2, v0
	v_add_u32_e32 v10, 0x2400, v0
	ds_read2_b32 v[0:1], v10 offset1:33
	s_waitcnt lgkmcnt(0)
	v_cvt_pk_bf16_f32 v0, v0, v1
	ds_read2_b32 v[2:3], v10 offset0:66 offset1:99
	s_waitcnt lgkmcnt(0)
	v_cvt_pk_bf16_f32 v1, v2, v3
	ds_read2_b32 v[2:3], v10 offset0:132 offset1:165
	s_waitcnt lgkmcnt(0)
	v_cvt_pk_bf16_f32 v2, v2, v3
	ds_read2_b32 v[6:7], v10 offset0:198 offset1:231
	s_waitcnt lgkmcnt(0)
	v_cvt_pk_bf16_f32 v3, v6, v7
	v_add_u32_e32 v6, s4, v9
	v_ashrrev_i32_e32 v7, 31, v6
	v_lshlrev_b64 v[6:7], 12, v[6:7]
	v_lshl_add_u64 v[6:7], v[4:5], 0, v[6:7]
	flat_store_dwordx4 v[6:7], v[0:3]
	ds_read2_b32 v[0:1], v10 offset0:8 offset1:41
	s_waitcnt lgkmcnt(0)
	v_cvt_pk_bf16_f32 v0, v0, v1
	ds_read2_b32 v[2:3], v10 offset0:74 offset1:107
	s_waitcnt lgkmcnt(0)
	v_cvt_pk_bf16_f32 v1, v2, v3
	ds_read2_b32 v[2:3], v10 offset0:140 offset1:173
	s_waitcnt lgkmcnt(0)
	v_cvt_pk_bf16_f32 v2, v2, v3
	ds_read2_b32 v[6:7], v10 offset0:206 offset1:239
	s_waitcnt lgkmcnt(0)
	v_cvt_pk_bf16_f32 v3, v6, v7
	v_add_u32_e32 v6, s4, v11
	v_ashrrev_i32_e32 v7, 31, v6
	v_lshlrev_b64 v[6:7], 12, v[6:7]
	v_lshl_add_u64 v[6:7], v[4:5], 0, v[6:7]
	flat_store_dwordx4 v[6:7], v[0:3]
	ds_read2_b32 v[0:1], v10 offset0:16 offset1:49
	s_waitcnt lgkmcnt(0)
	v_cvt_pk_bf16_f32 v0, v0, v1
	ds_read2_b32 v[2:3], v10 offset0:82 offset1:115
	s_waitcnt lgkmcnt(0)
	v_cvt_pk_bf16_f32 v1, v2, v3
	ds_read2_b32 v[2:3], v10 offset0:148 offset1:181
	s_waitcnt lgkmcnt(0)
	v_cvt_pk_bf16_f32 v2, v2, v3
	ds_read2_b32 v[6:7], v10 offset0:214 offset1:247
	s_waitcnt lgkmcnt(0)
	v_cvt_pk_bf16_f32 v3, v6, v7
	v_add_u32_e32 v6, s4, v12
	v_ashrrev_i32_e32 v7, 31, v6
	v_lshlrev_b64 v[6:7], 12, v[6:7]
	v_lshl_add_u64 v[6:7], v[4:5], 0, v[6:7]
	flat_store_dwordx4 v[6:7], v[0:3]
	ds_read2_b32 v[0:1], v10 offset0:24 offset1:57
	s_waitcnt lgkmcnt(0)
	v_cvt_pk_bf16_f32 v0, v0, v1
	ds_read2_b32 v[2:3], v10 offset0:90 offset1:123
	s_waitcnt lgkmcnt(0)
	v_cvt_pk_bf16_f32 v1, v2, v3
	ds_read2_b32 v[2:3], v10 offset0:156 offset1:189
	s_waitcnt lgkmcnt(0)
	v_cvt_pk_bf16_f32 v2, v2, v3
	ds_read2_b32 v[6:7], v10 offset0:222 offset1:255
	s_waitcnt lgkmcnt(0)
	v_cvt_pk_bf16_f32 v3, v6, v7
	v_add_u32_e32 v6, s4, v13
	v_ashrrev_i32_e32 v7, 31, v6
	v_lshlrev_b64 v[6:7], 12, v[6:7]
	v_lshl_add_u64 v[4:5], v[4:5], 0, v[6:7]
	flat_store_dwordx4 v[4:5], v[0:3]
	s_waitcnt lgkmcnt(0)
	s_mov_b64 s[4:5], 0

.LBB0_1220:
	s_andn2_b64 vcc, exec, s[4:5]
	s_cbranch_vccnz .LBB0_1222
	s_add_i32 s4, s38, 0xffff5000
	s_mul_i32 s5, s4, 0xba2f
	s_lshr_b32 s5, s5, 28
	s_mul_i32 s12, s5, 0xea00
	s_add_i32 s4, s12, s4
	s_sext_i32_i16 s12, s4
	s_bfe_u32 s12, s12, 0x60019
	s_add_i32 s12, s4, s12
	s_sext_i32_i16 s13, s12
	s_and_b32 s12, s12, 0xffc0
	s_sub_i32 s4, s4, s12
	v_readlane_b32 s12, v254, 6
	s_mul_i32 s21, s5, 0x2c00000
	s_mul_i32 s5, s5, 0x1600000
	v_mov_b32_e32 v0, s12
	ds_read_b64 v[0:1], v0
	s_sext_i32_i16 s4, s4
	v_ashrrev_i32_e32 v9, 3, v8
	s_waitcnt lgkmcnt(0)
	v_readfirstlane_b32 s20, v0
	v_readfirstlane_b32 s12, v1
	s_add_u32 s40, s20, s21
	s_addc_u32 s41, s12, 0
	s_add_u32 s5, s26, s5
	v_lshlrev_b32_e32 v0, 2, v8
	s_addc_u32 s20, s27, 0
	s_lshl_b32 s4, s4, 5
	s_and_b32 s12, s13, 0xffffffc0
	v_and_b32_e32 v1, 28, v0
	v_or_b32_e32 v0, s4, v1
	v_add_u32_e32 v6, s12, v9
	v_lshlrev_b32_e32 v10, 2, v1
	v_ashrrev_i32_e32 v1, 31, v0
	v_ashrrev_i32_e32 v7, 31, v6
	v_lshl_add_u64 v[4:5], v[0:1], 2, s[40:41]
	v_lshlrev_b64 v[0:1], 13, v[6:7]
	v_lshl_add_u64 v[0:1], v[4:5], 0, v[0:1]
	s_mov_b32 s100, 0x10000
	s_mov_b32 s101, 0
	v_lshl_add_u64 v[62:63], v[0:1], 0, s[100:101]
	global_load_dword v60, v[62:63], off
	v_lshl_add_u64 v[62:63], v[62:63], 0, s[100:101]
	global_load_dword v60, v[62:63], off
	v_lshl_add_u64 v[62:63], v[62:63], 0, s[100:101]
	global_load_dword v60, v[62:63], off
	v_lshl_add_u64 v[62:63], v[62:63], 0, s[100:101]
	global_load_dword v60, v[62:63], off
	v_lshl_add_u64 v[62:63], v[62:63], 0, s[100:101]
	global_load_dword v60, v[62:63], off
	v_lshl_add_u64 v[62:63], v[62:63], 0, s[100:101]
	global_load_dword v60, v[62:63], off
	v_lshl_add_u64 v[62:63], v[62:63], 0, s[100:101]
	global_load_dword v60, v[62:63], off
	flat_load_dwordx4 v[0:3], v[0:1]
	v_mul_lo_u32 v7, v9, s92
	v_add3_u32 v7, s17, v10, v7
	v_add_u32_e32 v10, 0x2400, v7
	v_add_u32_e32 v11, 0x2820, v7
	v_add_u32_e32 v12, 0x2c40, v7
	v_add_u32_e32 v13, 0x3060, v7
	s_ashr_i32 s13, s12, 31
	s_waitcnt vmcnt(0) lgkmcnt(0)
	ds_write2_b32 v10, v0, v1 offset1:1
	v_add_u32_e32 v0, 0x2408, v7
	v_add_u32_e32 v10, 8, v9
	ds_write2_b32 v0, v2, v3 offset1:1
	v_add_u32_e32 v0, s12, v10
	v_ashrrev_i32_e32 v1, 31, v0
	v_lshlrev_b64 v[0:1], 13, v[0:1]
	v_lshl_add_u64 v[0:1], v[4:5], 0, v[0:1]
	flat_load_dwordx4 v[0:3], v[0:1]
	s_waitcnt vmcnt(0) lgkmcnt(0)
	ds_write2_b32 v11, v0, v1 offset1:1
	v_add_u32_e32 v0, 0x2828, v7
	v_add_u32_e32 v11, 16, v9
	ds_write2_b32 v0, v2, v3 offset1:1
	v_add_u32_e32 v0, s12, v11
	v_ashrrev_i32_e32 v1, 31, v0
	v_lshlrev_b64 v[0:1], 13, v[0:1]
	v_lshl_add_u64 v[0:1], v[4:5], 0, v[0:1]
	flat_load_dwordx4 v[0:3], v[0:1]
	s_waitcnt vmcnt(0) lgkmcnt(0)
	ds_write2_b32 v12, v0, v1 offset1:1
	v_add_u32_e32 v0, 0x2c48, v7
	v_add_u32_e32 v12, 24, v9
	ds_write2_b32 v0, v2, v3 offset1:1
	v_add_u32_e32 v0, s12, v12
	v_ashrrev_i32_e32 v1, 31, v0
	v_lshlrev_b64 v[0:1], 13, v[0:1]
	v_lshl_add_u64 v[0:1], v[4:5], 0, v[0:1]
	flat_load_dwordx4 v[0:3], v[0:1]
	s_lshl_b64 s[12:13], s[12:13], 1
	s_add_u32 s12, s5, s12
	s_addc_u32 s13, s20, s13
	s_movk_i32 s5, 0x2c00
	s_waitcnt vmcnt(0) lgkmcnt(0)
	ds_write2_b32 v13, v0, v1 offset1:1
	v_add_u32_e32 v0, 0x3068, v7
	ds_write2_b32 v0, v2, v3 offset1:1
	v_add_u32_e32 v0, 32, v6
	v_ashrrev_i32_e32 v1, 31, v0
	v_lshlrev_b64 v[0:1], 13, v[0:1]
	v_lshl_add_u64 v[0:1], v[4:5], 0, v[0:1]
	flat_load_dwordx4 v[0:3], v[0:1]
	v_add_u32_e32 v13, 0x3480, v7
	s_waitcnt vmcnt(0) lgkmcnt(0)
	ds_write2_b32 v13, v0, v1 offset1:1
	v_add_u32_e32 v0, 0x3488, v7
	ds_write2_b32 v0, v2, v3 offset1:1
	v_add_u32_e32 v0, 40, v6
	v_ashrrev_i32_e32 v1, 31, v0
	v_lshlrev_b64 v[0:1], 13, v[0:1]
	v_lshl_add_u64 v[0:1], v[4:5], 0, v[0:1]
	flat_load_dwordx4 v[0:3], v[0:1]
	v_add_u32_e32 v13, 0x38a0, v7
	s_waitcnt vmcnt(0) lgkmcnt(0)
	ds_write2_b32 v13, v0, v1 offset1:1
	v_add_u32_e32 v0, 0x38a8, v7
	ds_write2_b32 v0, v2, v3 offset1:1
	v_add_u32_e32 v0, 48, v6
	v_ashrrev_i32_e32 v1, 31, v0
	v_lshlrev_b64 v[0:1], 13, v[0:1]
	v_lshl_add_u64 v[0:1], v[4:5], 0, v[0:1]
	flat_load_dwordx4 v[0:3], v[0:1]
	v_add_u32_e32 v13, 0x3cc0, v7
	s_waitcnt vmcnt(0) lgkmcnt(0)
	ds_write2_b32 v13, v0, v1 offset1:1
	v_add_u32_e32 v0, 0x3cc8, v7
	ds_write2_b32 v0, v2, v3 offset1:1
	v_add_u32_e32 v0, 56, v6
	v_ashrrev_i32_e32 v1, 31, v0
	v_lshlrev_b64 v[0:1], 13, v[0:1]
	v_lshl_add_u64 v[0:1], v[4:5], 0, v[0:1]
	flat_load_dwordx4 v[0:3], v[0:1]
	v_add_u32_e32 v4, 0x40e0, v7
	s_waitcnt vmcnt(0) lgkmcnt(0)
	ds_write2_b32 v4, v0, v1 offset1:1
	v_add_u32_e32 v0, 0x40e8, v7
	ds_write2_b32 v0, v2, v3 offset1:1
	v_lshlrev_b32_e32 v0, 3, v8
	v_and_b32_e32 v0, 56, v0
	v_mul_u32_u24_e32 v2, 0x84, v0
	v_lshlrev_b32_e32 v0, 1, v0
	v_mov_b32_e32 v1, v16
	v_lshl_add_u64 v[4:5], s[12:13], 0, v[0:1]
	v_lshlrev_b32_e32 v0, 2, v9
	s_waitcnt lgkmcnt(0)
	v_add3_u32 v0, s17, v2, v0
	v_add_u32_e32 v13, 0x2400, v0
	ds_read2_b32 v[0:1], v13 offset1:33
	s_waitcnt lgkmcnt(0)
	v_cvt_pk_bf16_f32 v0, v0, v1
	ds_read2_b32 v[2:3], v13 offset0:66 offset1:99
	s_waitcnt lgkmcnt(0)
	v_cvt_pk_bf16_f32 v1, v2, v3
	ds_read2_b32 v[2:3], v13 offset0:132 offset1:165
	s_waitcnt lgkmcnt(0)
	v_cvt_pk_bf16_f32 v2, v2, v3
	ds_read2_b32 v[6:7], v13 offset0:198 offset1:231
	s_waitcnt lgkmcnt(0)
	v_cvt_pk_bf16_f32 v3, v6, v7
	v_add_u32_e32 v6, s4, v9
	v_mad_i64_i32 v[6:7], s[12:13], v6, s5, v[4:5]
	flat_store_dwordx4 v[6:7], v[0:3]
	ds_read2_b32 v[0:1], v13 offset0:8 offset1:41
	s_waitcnt lgkmcnt(0)
	v_cvt_pk_bf16_f32 v0, v0, v1
	ds_read2_b32 v[2:3], v13 offset0:74 offset1:107
	s_waitcnt lgkmcnt(0)
	v_cvt_pk_bf16_f32 v1, v2, v3
	ds_read2_b32 v[2:3], v13 offset0:140 offset1:173
	s_waitcnt lgkmcnt(0)
	v_cvt_pk_bf16_f32 v2, v2, v3
	ds_read2_b32 v[6:7], v13 offset0:206 offset1:239
	s_waitcnt lgkmcnt(0)
	v_cvt_pk_bf16_f32 v3, v6, v7
	v_add_u32_e32 v6, s4, v10
	v_mad_i64_i32 v[6:7], s[12:13], v6, s5, v[4:5]
	flat_store_dwordx4 v[6:7], v[0:3]
	ds_read2_b32 v[0:1], v13 offset0:16 offset1:49
	s_waitcnt lgkmcnt(0)
	v_cvt_pk_bf16_f32 v0, v0, v1
	ds_read2_b32 v[2:3], v13 offset0:82 offset1:115
	s_waitcnt lgkmcnt(0)
	v_cvt_pk_bf16_f32 v1, v2, v3
	ds_read2_b32 v[2:3], v13 offset0:148 offset1:181
	s_waitcnt lgkmcnt(0)
	v_cvt_pk_bf16_f32 v2, v2, v3
	ds_read2_b32 v[6:7], v13 offset0:214 offset1:247
	s_waitcnt lgkmcnt(0)
	v_cvt_pk_bf16_f32 v3, v6, v7
	v_add_u32_e32 v6, s4, v11
	v_mad_i64_i32 v[6:7], s[12:13], v6, s5, v[4:5]
	flat_store_dwordx4 v[6:7], v[0:3]
	ds_read2_b32 v[0:1], v13 offset0:24 offset1:57
	s_waitcnt lgkmcnt(0)
	v_cvt_pk_bf16_f32 v0, v0, v1
	ds_read2_b32 v[2:3], v13 offset0:90 offset1:123
	s_waitcnt lgkmcnt(0)
	v_cvt_pk_bf16_f32 v1, v2, v3
	ds_read2_b32 v[2:3], v13 offset0:156 offset1:189
	s_waitcnt lgkmcnt(0)
	v_cvt_pk_bf16_f32 v2, v2, v3
	ds_read2_b32 v[6:7], v13 offset0:222 offset1:255
	s_waitcnt lgkmcnt(0)
	v_cvt_pk_bf16_f32 v3, v6, v7
	v_add_u32_e32 v6, s4, v12
	v_mad_i64_i32 v[4:5], s[4:5], v6, s5, v[4:5]
	flat_store_dwordx4 v[4:5], v[0:3]
	s_waitcnt lgkmcnt(0)
